# residual GEMMs: blocks with a K-split sub-unit run it before their whole-K tile (partial stores drain under the main K-loop)
# speedup vs baseline: 1.0095x; 1.0095x over previous
.LBB0_108:
	s_xor_b64 s[2:3], s[8:9], -1
	v_writelane_b32 v240, s2, 55
	v_mov_b32_e32 v12, v147
	s_mov_b32 s18, -1
	v_writelane_b32 v240, s3, 56
	s_and_b64 s[2:3], s[8:9], exec
	s_cselect_b32 s3, s5, 64
	s_ashr_i32 s2, s53, 31
	s_lshr_b32 s2, s2, 24
	s_add_i32 s2, s53, s2
	s_ashr_i32 s82, s2, 8
	s_lshr_b32 s2, s34, 6
	v_writelane_b32 v240, s3, 57
	s_cmp_gt_i32 s46, -1
	s_mul_i32 s8, s3, s82
	v_writelane_b32 v240, s2, 58
	v_readfirstlane_b32 s7, v12
	s_mov_b64 s[2:3], 0
	s_mov_b32 s6, 0
	s_cselect_b64 s[10:11], -1, 0
	s_cmp_lt_i32 s46, 0
	s_mov_b32 s47, 0
	s_mov_b32 s19, 0
	s_mov_b32 s48, s49
	v_readlane_b32 s12, v243, 21
	v_readlane_b32 s9, v243, 23
	v_readlane_b32 s13, v243, 22
	v_readlane_b32 s9, v241, 30
	s_cbranch_scc1 .LBB0_122
	s_mov_b32 s14, s46
	s_cmp_eq_u32 s44, 0
	s_cbranch_scc1 .Lus_first
	s_cmp_lt_u32 s46, 64
	s_cbranch_scc0 .Lus_first
	s_add_i32 s14, s46, s45
.Lus_first:
	s_cmp_lt_i32 s14, s8
	s_mov_b64 s[12:13], -1
	s_cbranch_scc1 .LBB0_116
	v_readlane_b32 s2, v240, 55
	v_readlane_b32 s3, v240, 56
	s_andn2_b64 vcc, exec, s[2:3]
	s_mov_b64 s[12:13], 0
	s_cbranch_vccnz .LBB0_113
	s_sub_i32 s3, s5, 64
	s_mul_i32 s3, s3, s82
	s_sub_i32 s2, s14, s8
	s_mul_i32 s3, s3, s44
	s_cmp_ge_i32 s2, s3
	s_cbranch_scc1 .LBB0_114
	v_cvt_f32_u32_e32 v0, s44
	s_sub_i32 s9, 0, s44
	s_abs_i32 s6, s2
	s_ashr_i32 s3, s2, 31
	v_rcp_iflag_f32_e32 v0, v0
	s_ff1_i32_b32 s14, s44
	v_mul_f32_e32 v0, 0x4f7ffffe, v0
	v_cvt_u32_f32_e32 v0, v0
	s_nop 0
	v_readfirstlane_b32 s15, v0
	s_mul_i32 s9, s9, s15
	s_mul_hi_u32 s9, s15, s9
	s_add_i32 s15, s15, s9
	s_mul_hi_u32 s9, s6, s15
	s_mul_i32 s15, s9, s44
	s_sub_i32 s6, s6, s15
	s_add_i32 s18, s9, 1
	s_sub_i32 s15, s6, s44
	s_cmp_ge_u32 s6, s44
	s_cselect_b32 s9, s18, s9
	s_cselect_b32 s6, s15, s6
	s_add_i32 s15, s9, 1
	s_cmp_ge_u32 s6, s44
	s_cselect_b32 s6, s15, s9
	s_abs_i32 s15, s82
	v_cvt_f32_u32_e32 v0, s15
	s_xor_b32 s6, s6, s3
	s_sub_i32 s3, s6, s3
	s_mul_i32 s6, s3, s44
	v_rcp_iflag_f32_e32 v0, v0
	s_sub_i32 s18, s2, s6
	s_bfe_u32 s2, s34, 0x80007
	s_lshr_b32 s19, s2, s14
	v_mul_f32_e32 v0, 0x4f7ffffe, v0
	v_cvt_u32_f32_e32 v0, v0
	s_sub_i32 s14, 0, s15
	s_abs_i32 s6, s3
	s_lshr_b32 s9, s34, 7
	v_readfirstlane_b32 s23, v0
	s_mul_i32 s14, s14, s23
	s_mul_hi_u32 s14, s23, s14
	s_add_i32 s23, s23, s14
	s_mul_hi_u32 s14, s6, s23
	s_add_i32 s2, s44, 31
	s_mul_i32 s23, s14, s15
	s_and_b32 s9, s2, s9
	s_xor_b32 s2, s3, s82
	s_sub_i32 s6, s6, s23
	s_ashr_i32 s2, s2, 31
	s_add_i32 s23, s14, 1
	s_sub_i32 s38, s6, s15
	s_cmp_ge_u32 s6, s15
	s_cselect_b32 s14, s23, s14
	s_cselect_b32 s6, s38, s6
	s_add_i32 s23, s14, 1
	s_cmp_ge_u32 s6, s15
	s_cselect_b32 s6, s23, s14
	s_xor_b32 s6, s6, s2
	s_sub_i32 s2, s6, s2
	s_add_i32 s6, s2, 64
	s_mul_i32 s2, s2, s82
	s_sub_i32 s47, s3, s2
	s_cmp_lt_i32 s18, s9
	s_mul_i32 s14, s18, s19
	s_cselect_b64 s[2:3], -1, 0
	s_min_i32 s9, s18, s9
	s_add_i32 s9, s9, s14
	s_lshl_b32 s14, s9, 1
	s_cmp_lg_u64 s[2:3], 0
	s_addc_u32 s2, s19, 0
	s_ashr_i32 s15, s14, 31
	s_lshl_b32 s19, s2, 1
	s_lshl_b64 s[2:3], s[14:15], 7
	s_branch .LBB0_116

.LBB0_130:
	s_andn2_b64 vcc, exec, s[10:11]
	s_add_i32 s59, s59, 1
	s_cbranch_vccnz .LBB0_135
	v_readlane_b32 s7, v240, 63
	s_mul_i32 s23, s59, s7
	s_mul_hi_u32 s34, s59, s45
	s_add_i32 s34, s34, s23
	s_mul_i32 s23, s59, s45
	s_cmp_eq_u32 s44, 0
	s_cbranch_scc1 .Lus_next
	s_cmp_lt_u32 s46, 64
	s_cbranch_scc0 .Lus_next
	s_cmp_eq_u32 s59, 1
	s_cbranch_scc0 .Lus_next
	s_mov_b32 s23, 0
	s_mov_b32 s34, 0
.Lus_next:
	s_add_u32 s38, s23, s46
	v_readlane_b32 s7, v179, 0
	s_addc_u32 s39, s34, s7
	v_mov_b64_e32 v[0:1], s[8:9]
	v_cmp_lt_i64_e32 vcc, s[38:39], v[0:1]
	s_mov_b64 s[88:89], -1
	s_and_b64 vcc, exec, vcc
	s_cbranch_vccnz .LBB0_139
	v_readlane_b32 s82, v240, 55
	v_readlane_b32 s83, v240, 56
	s_andn2_b64 vcc, exec, s[82:83]
	s_mov_b64 s[88:89], 0
	s_cbranch_vccnz .LBB0_136
	s_sub_i32 s23, s38, s8
	v_readlane_b32 s7, v179, 1
	s_cmp_ge_i32 s23, s7
	s_cbranch_scc1 .LBB0_137
	s_abs_i32 s39, s23
	v_readlane_b32 s7, v179, 8
	s_mul_hi_u32 s49, s39, s7
	s_mul_i32 s56, s49, s44
	s_sub_i32 s39, s39, s56
	s_ashr_i32 s34, s23, 31
	s_add_i32 s56, s49, 1
	s_sub_i32 s82, s39, s44
	s_cmp_ge_u32 s39, s44
	s_cselect_b32 s49, s56, s49
	s_cselect_b32 s39, s82, s39
	s_add_i32 s56, s49, 1
	s_cmp_ge_u32 s39, s44
	s_cselect_b32 s39, s56, s49
	s_xor_b32 s39, s39, s34
	s_sub_i32 s34, s39, s34
	s_mul_i32 s39, s34, s44
	s_sub_i32 s56, s23, s39
	s_ashr_i32 s23, s34, 31
	v_readlane_b32 s7, v179, 10
	s_xor_b32 s23, s23, s7
	s_abs_i32 s39, s34
	v_readlane_b32 s7, v179, 12
	s_mul_hi_u32 s49, s39, s7
	v_readlane_b32 s7, v179, 11
	s_mul_i32 s82, s49, s7
	s_sub_i32 s39, s39, s82
	s_add_i32 s82, s49, 1
	s_sub_i32 s83, s39, s7
	s_cmp_ge_u32 s39, s7
	s_cselect_b32 s49, s82, s49
	s_cselect_b32 s39, s83, s39
	s_add_i32 s82, s49, 1
	s_cmp_ge_u32 s39, s7
	s_cselect_b32 s39, s82, s49
	s_xor_b32 s39, s39, s23
	s_sub_i32 s39, s39, s23
	v_readlane_b32 s7, v179, 13
	s_add_i32 s23, s39, 64
	s_mul_i32 s39, s39, s7
	s_sub_i32 s98, s34, s39
	v_readlane_b32 s39, v179, 3
	v_readlane_b32 s7, v179, 2
	s_cmp_lt_i32 s56, s39
	s_mul_i32 s34, s56, s7
	s_cselect_b64 s[90:91], -1, 0
	s_min_i32 s39, s56, s39
	s_add_i32 s39, s39, s34
	s_lshl_b32 s96, s39, 1
	s_cmp_lg_u64 s[90:91], 0
	s_addc_u32 s34, s7, 0
	s_ashr_i32 s97, s96, 31
	s_lshl_b32 s49, s34, 1
	s_lshl_b64 s[96:97], s[96:97], 7
	s_branch .LBB0_139
